# up, down and transposed in-proj GEMMs: first K-loop iteration peeled with C=0 first-touch MFMAs; accumulator zeroing removed (as for in-proj main)
# speedup vs baseline: 1.0060x; 1.0060x over previous
.LBB0_105:
	s_ashr_i32 s71, s70, 31
	s_lshl_b64 s[6:7], s[70:71], 19
	v_readlane_b32 s28, v254, 41
	v_readlane_b32 s29, v254, 42
	s_add_u32 s72, s28, s6
	s_addc_u32 s73, s29, s7
	s_and_b64 s[6:7], s[40:41], exec
	s_cselect_b32 s6, s73, s5
	s_cselect_b32 s7, s72, s4
	s_ashr_i32 s69, s68, 31
	s_lshl_b64 s[28:29], s[68:69], 19
	s_add_u32 s74, s9, s28
	s_addc_u32 s75, s10, s29
	s_and_b64 s[28:29], s[40:41], exec
	s_cselect_b32 s27, s75, s1
	s_cselect_b32 s28, s74, s0
	s_add_u32 s42, s4, 0x40080
	s_addc_u32 s43, s5, 0
	s_add_u32 s29, s0, 0x100
	s_addc_u32 s34, s1, 0
	s_mov_b32 s35, -2
	s_waitcnt vmcnt(0)
	s_mov_b64 s[80:81], 0x80
	s_add_u32 s0, s42, 0xfffc0080
	s_addc_u32 s1, s43, -1
	s_add_i32 s46, 0, 0x10000
	s_cmp_eq_u32 s35, 12
	s_cselect_b32 s5, s6, s1
	s_cselect_b32 s4, s7, s0
	v_add_u32_e32 v0, s46, v223
	s_cselect_b32 s1, s27, s34
	s_cselect_b32 s0, s28, s29
	s_add_i32 s50, 0, 0x14000
	ds_read_b128 v[130:133], v0
	ds_read_b128 v[134:137], v0 offset:1024
	ds_read_b128 v[150:153], v0 offset:2048
	ds_read_b128 v[154:157], v0 offset:3072
	v_add_u32_e32 v0, s50, v223
	ds_read_b128 v[170:173], v0
	ds_read_b128 v[174:177], v0 offset:1024
	ds_read_b128 v[178:181], v0 offset:2048
	ds_read_b128 v[182:185], v0 offset:3072
	v_lshl_add_u64 v[158:159], s[42:43], 0, v[146:147]
	s_add_i32 m0, s13, 0xc000
	ds_read_b128 v[186:189], v225
	ds_read_b128 v[190:193], v225 offset:1024
	ds_read_b128 v[194:197], v225 offset:2048
	ds_read_b128 v[198:201], v225 offset:3072
	ds_read_b128 v[202:205], v225 offset:4096
	ds_read_b128 v[226:229], v225 offset:5120
	ds_read_b128 v[230:233], v225 offset:6144
	ds_read_b128 v[234:237], v225 offset:7168
	global_load_lds_dwordx4 v[158:159], off
	v_lshl_add_u64 v[158:159], s[42:43], 0, v[148:149]
	s_add_i32 m0, s13, 0xe000
	s_nop 0
	global_load_lds_dwordx4 v[158:159], off
	s_cmp_lg_u32 s35, -2
	s_cbranch_scc1 .Lpwt__106_0
	s_cmp_lt_u32 s26, 2
	s_cbranch_scc0 .Lpws__106_0

.Lpws__106_0:
	s_waitcnt lgkmcnt(0)
	s_barrier
	s_setprio 1
	s_waitcnt lgkmcnt(0)
	v_mfma_f32_16x16x32_bf16 v[126:129], v[130:133], v[186:189], 0
	v_mfma_f32_16x16x32_bf16 v[62:65], v[150:153], v[186:189], 0
	v_mfma_f32_16x16x32_bf16 v[110:113], v[130:133], v[194:197], 0
	v_mfma_f32_16x16x32_bf16 v[46:49], v[150:153], v[194:197], 0
	v_mfma_f32_16x16x32_bf16 v[106:109], v[130:133], v[202:205], 0
	v_mfma_f32_16x16x32_bf16 v[42:45], v[150:153], v[202:205], 0
	v_mfma_f32_16x16x32_bf16 v[118:121], v[130:133], v[230:233], 0
	v_mfma_f32_16x16x32_bf16 v[54:57], v[150:153], v[230:233], 0
	v_mfma_f32_16x16x32_bf16 v[126:129], v[134:137], v[190:193], v[126:129]
	v_mfma_f32_16x16x32_bf16 v[62:65], v[154:157], v[190:193], v[62:65]
	v_mfma_f32_16x16x32_bf16 v[110:113], v[134:137], v[198:201], v[110:113]
	v_mfma_f32_16x16x32_bf16 v[46:49], v[154:157], v[198:201], v[46:49]
	v_mfma_f32_16x16x32_bf16 v[106:109], v[134:137], v[226:229], v[106:109]
	v_mfma_f32_16x16x32_bf16 v[42:45], v[154:157], v[226:229], v[42:45]
	v_mfma_f32_16x16x32_bf16 v[118:121], v[134:137], v[234:237], v[118:121]
	v_mfma_f32_16x16x32_bf16 v[54:57], v[154:157], v[234:237], v[54:57]
	s_setprio 0
	s_setprio 1
	v_mfma_f32_16x16x32_bf16 v[122:125], v[170:173], v[186:189], 0
	v_mfma_f32_16x16x32_bf16 v[58:61], v[178:181], v[186:189], 0
	v_mfma_f32_16x16x32_bf16 v[102:105], v[170:173], v[194:197], 0
	v_mfma_f32_16x16x32_bf16 v[38:41], v[178:181], v[194:197], 0
	v_mfma_f32_16x16x32_bf16 v[98:101], v[170:173], v[202:205], 0
	v_mfma_f32_16x16x32_bf16 v[34:37], v[178:181], v[202:205], 0
	v_mfma_f32_16x16x32_bf16 v[114:117], v[170:173], v[230:233], 0
	v_mfma_f32_16x16x32_bf16 v[50:53], v[178:181], v[230:233], 0
	v_mfma_f32_16x16x32_bf16 v[122:125], v[174:177], v[190:193], v[122:125]
	v_mfma_f32_16x16x32_bf16 v[58:61], v[182:185], v[190:193], v[58:61]
	v_mfma_f32_16x16x32_bf16 v[102:105], v[174:177], v[198:201], v[102:105]
	v_mfma_f32_16x16x32_bf16 v[38:41], v[182:185], v[198:201], v[38:41]
	v_mfma_f32_16x16x32_bf16 v[98:101], v[174:177], v[226:229], v[98:101]
	v_mfma_f32_16x16x32_bf16 v[34:37], v[182:185], v[226:229], v[34:37]
	v_mfma_f32_16x16x32_bf16 v[114:117], v[174:177], v[234:237], v[114:117]
	v_mfma_f32_16x16x32_bf16 v[50:53], v[182:185], v[234:237], v[50:53]
	s_setprio 0
	s_barrier
	s_add_i32 s46, s46, s12
	v_lshl_add_u64 v[158:159], s[0:1], 0, v[140:141]
	s_mov_b32 m0, s46
	ds_read_b128 v[186:189], v225 offset:16384
	ds_read_b128 v[190:193], v225 offset:17408
	ds_read_b128 v[194:197], v225 offset:18432
	ds_read_b128 v[198:201], v225 offset:19456
	ds_read_b128 v[202:205], v225 offset:20480
	ds_read_b128 v[226:229], v225 offset:21504
	ds_read_b128 v[230:233], v225 offset:22528
	ds_read_b128 v[234:237], v225 offset:23552
	global_load_lds_dwordx4 v[158:159], off
	s_add_i32 m0, s46, 0x2000
	s_add_u32 s46, s0, 0x40000
	v_lshl_add_u64 v[206:207], s[0:1], 0, v[144:145]
	s_addc_u32 s47, s1, 0
	s_add_i32 s50, s50, s12
	global_load_lds_dwordx4 v[206:207], off
	v_lshl_add_u64 v[238:239], s[46:47], 0, v[140:141]
	s_mov_b32 m0, s50
	v_lshl_add_u64 v[240:241], s[4:5], 0, v[142:143]
	global_load_lds_dwordx4 v[238:239], off
	v_lshl_add_u64 v[238:239], s[46:47], 0, v[144:145]
	s_add_i32 m0, s50, 0x2000
	s_nop 0
	global_load_lds_dwordx4 v[238:239], off
	v_lshl_add_u64 v[238:239], s[4:5], 0, v[138:139]
	s_mov_b32 m0, s13
	s_nop 0
	global_load_lds_dwordx4 v[238:239], off
	s_mov_b32 m0, s14
	s_nop 0
	global_load_lds_dwordx4 v[240:241], off
	s_cmp_lg_u32 s35, -2
	s_cbranch_scc1 .Lpwt__106_1
	s_cmp_lt_u32 s26, 2
	s_cbranch_scc0 .Lpws__106_1

.Lpws__106_1:
	s_waitcnt lgkmcnt(0)
	s_barrier
	s_setprio 1
	s_waitcnt lgkmcnt(0)
	v_mfma_f32_16x16x32_bf16 v[94:97], v[130:133], v[186:189], 0
	v_mfma_f32_16x16x32_bf16 v[30:33], v[150:153], v[186:189], 0
	v_mfma_f32_16x16x32_bf16 v[78:81], v[130:133], v[194:197], 0
	v_mfma_f32_16x16x32_bf16 v[18:21], v[150:153], v[194:197], 0
	v_mfma_f32_16x16x32_bf16 v[74:77], v[130:133], v[202:205], 0
	v_mfma_f32_16x16x32_bf16 v[10:13], v[150:153], v[202:205], 0
	v_mfma_f32_16x16x32_bf16 v[86:89], v[130:133], v[230:233], 0
	v_mfma_f32_16x16x32_bf16 v[22:25], v[150:153], v[230:233], 0
	v_mfma_f32_16x16x32_bf16 v[94:97], v[134:137], v[190:193], v[94:97]
	v_mfma_f32_16x16x32_bf16 v[30:33], v[154:157], v[190:193], v[30:33]
	v_mfma_f32_16x16x32_bf16 v[78:81], v[134:137], v[198:201], v[78:81]
	v_mfma_f32_16x16x32_bf16 v[18:21], v[154:157], v[198:201], v[18:21]
	v_mfma_f32_16x16x32_bf16 v[74:77], v[134:137], v[226:229], v[74:77]
	v_mfma_f32_16x16x32_bf16 v[10:13], v[154:157], v[226:229], v[10:13]
	v_mfma_f32_16x16x32_bf16 v[86:89], v[134:137], v[234:237], v[86:89]
	v_mfma_f32_16x16x32_bf16 v[22:25], v[154:157], v[234:237], v[22:25]
	s_setprio 0
	s_setprio 1
	v_mfma_f32_16x16x32_bf16 v[90:93], v[170:173], v[186:189], 0
	v_mfma_f32_16x16x32_bf16 v[26:29], v[178:181], v[186:189], 0
	v_mfma_f32_16x16x32_bf16 v[70:73], v[170:173], v[194:197], 0
	v_mfma_f32_16x16x32_bf16 v[6:9], v[178:181], v[194:197], 0
	v_mfma_f32_16x16x32_bf16 v[66:69], v[170:173], v[202:205], 0
	v_mfma_f32_16x16x32_bf16 v[2:5], v[178:181], v[202:205], 0
	v_mfma_f32_16x16x32_bf16 v[82:85], v[170:173], v[230:233], 0
	v_mfma_f32_16x16x32_bf16 v[14:17], v[178:181], v[230:233], 0
	v_mfma_f32_16x16x32_bf16 v[90:93], v[174:177], v[190:193], v[90:93]
	v_mfma_f32_16x16x32_bf16 v[26:29], v[182:185], v[190:193], v[26:29]
	v_mfma_f32_16x16x32_bf16 v[70:73], v[174:177], v[198:201], v[70:73]
	v_mfma_f32_16x16x32_bf16 v[6:9], v[182:185], v[198:201], v[6:9]
	v_mfma_f32_16x16x32_bf16 v[66:69], v[174:177], v[226:229], v[66:69]
	v_mfma_f32_16x16x32_bf16 v[2:5], v[182:185], v[226:229], v[2:5]
	v_mfma_f32_16x16x32_bf16 v[82:85], v[174:177], v[234:237], v[82:85]
	v_mfma_f32_16x16x32_bf16 v[14:17], v[182:185], v[234:237], v[14:17]
	s_setprio 0
	s_barrier
	s_add_i32 s46, 0, 0x18000
	v_add_u32_e32 v0, s46, v223
	s_add_i32 s47, 0, 0x1c000
	ds_read_b128 v[130:133], v0
	ds_read_b128 v[134:137], v0 offset:1024
	ds_read_b128 v[150:153], v0 offset:2048
	ds_read_b128 v[154:157], v0 offset:3072
	v_add_u32_e32 v0, s47, v223
	ds_read_b128 v[170:173], v0
	ds_read_b128 v[174:177], v0 offset:1024
	ds_read_b128 v[178:181], v0 offset:2048
	ds_read_b128 v[182:185], v0 offset:3072
	s_add_u32 s4, s4, 0x40000
	s_addc_u32 s5, s5, 0
	s_mov_b32 m0, s15
	v_lshl_add_u64 v[242:243], s[4:5], 0, v[138:139]
	ds_read_b128 v[186:189], v225 offset:32768
	ds_read_b128 v[190:193], v225 offset:33792
	ds_read_b128 v[194:197], v225 offset:34816
	ds_read_b128 v[198:201], v225 offset:35840
	ds_read_b128 v[202:205], v225 offset:36864
	ds_read_b128 v[226:229], v225 offset:37888
	ds_read_b128 v[230:233], v225 offset:38912
	ds_read_b128 v[234:237], v225 offset:39936
	global_load_lds_dwordx4 v[242:243], off
	v_lshl_add_u64 v[242:243], s[4:5], 0, v[142:143]
	s_mov_b32 m0, s16
	s_nop 0
	global_load_lds_dwordx4 v[242:243], off
	s_waitcnt vmcnt(8)
	s_waitcnt lgkmcnt(0)
	s_barrier
	s_setprio 1
	s_waitcnt lgkmcnt(0)
	v_mfma_f32_16x16x32_bf16 v[126:129], v[130:133], v[186:189], v[126:129]
	v_mfma_f32_16x16x32_bf16 v[62:65], v[150:153], v[186:189], v[62:65]
	v_mfma_f32_16x16x32_bf16 v[110:113], v[130:133], v[194:197], v[110:113]
	v_mfma_f32_16x16x32_bf16 v[46:49], v[150:153], v[194:197], v[46:49]
	v_mfma_f32_16x16x32_bf16 v[106:109], v[130:133], v[202:205], v[106:109]
	v_mfma_f32_16x16x32_bf16 v[42:45], v[150:153], v[202:205], v[42:45]
	v_mfma_f32_16x16x32_bf16 v[118:121], v[130:133], v[230:233], v[118:121]
	v_mfma_f32_16x16x32_bf16 v[54:57], v[150:153], v[230:233], v[54:57]
	v_mfma_f32_16x16x32_bf16 v[126:129], v[134:137], v[190:193], v[126:129]
	v_mfma_f32_16x16x32_bf16 v[62:65], v[154:157], v[190:193], v[62:65]
	v_mfma_f32_16x16x32_bf16 v[110:113], v[134:137], v[198:201], v[110:113]
	v_mfma_f32_16x16x32_bf16 v[46:49], v[154:157], v[198:201], v[46:49]
	v_mfma_f32_16x16x32_bf16 v[106:109], v[134:137], v[226:229], v[106:109]
	v_mfma_f32_16x16x32_bf16 v[42:45], v[154:157], v[226:229], v[42:45]
	v_mfma_f32_16x16x32_bf16 v[118:121], v[134:137], v[234:237], v[118:121]
	v_mfma_f32_16x16x32_bf16 v[54:57], v[154:157], v[234:237], v[54:57]
	s_setprio 0
	s_setprio 1
	v_mfma_f32_16x16x32_bf16 v[122:125], v[170:173], v[186:189], v[122:125]
	v_mfma_f32_16x16x32_bf16 v[58:61], v[178:181], v[186:189], v[58:61]
	v_mfma_f32_16x16x32_bf16 v[102:105], v[170:173], v[194:197], v[102:105]
	v_mfma_f32_16x16x32_bf16 v[38:41], v[178:181], v[194:197], v[38:41]
	v_mfma_f32_16x16x32_bf16 v[98:101], v[170:173], v[202:205], v[98:101]
	v_mfma_f32_16x16x32_bf16 v[34:37], v[178:181], v[202:205], v[34:37]
	v_mfma_f32_16x16x32_bf16 v[114:117], v[170:173], v[230:233], v[114:117]
	v_mfma_f32_16x16x32_bf16 v[50:53], v[178:181], v[230:233], v[50:53]
	v_mfma_f32_16x16x32_bf16 v[122:125], v[174:177], v[190:193], v[122:125]
	v_mfma_f32_16x16x32_bf16 v[58:61], v[182:185], v[190:193], v[58:61]
	v_mfma_f32_16x16x32_bf16 v[102:105], v[174:177], v[198:201], v[102:105]
	v_mfma_f32_16x16x32_bf16 v[38:41], v[182:185], v[198:201], v[38:41]
	v_mfma_f32_16x16x32_bf16 v[98:101], v[174:177], v[226:229], v[98:101]
	v_mfma_f32_16x16x32_bf16 v[34:37], v[182:185], v[226:229], v[34:37]
	v_mfma_f32_16x16x32_bf16 v[114:117], v[174:177], v[234:237], v[114:117]
	v_mfma_f32_16x16x32_bf16 v[50:53], v[182:185], v[234:237], v[50:53]
	s_setprio 0
	s_barrier
	s_add_i32 s4, s46, s12
	v_lshl_add_u64 v[158:159], v[158:159], 0, s[80:81]
	s_mov_b32 m0, s4
	ds_read_b128 v[186:189], v225 offset:49152
	ds_read_b128 v[190:193], v225 offset:50176
	ds_read_b128 v[194:197], v225 offset:51200
	ds_read_b128 v[198:201], v225 offset:52224
	ds_read_b128 v[202:205], v225 offset:53248
	ds_read_b128 v[226:229], v225 offset:54272
	ds_read_b128 v[230:233], v225 offset:55296
	ds_read_b128 v[234:237], v225 offset:56320
	global_load_lds_dwordx4 v[158:159], off
	s_add_i32 m0, s4, 0x2000
	s_add_u32 s0, s0, 0x40080
	v_lshl_add_u64 v[158:159], v[206:207], 0, s[80:81]
	s_addc_u32 s1, s1, 0
	s_add_i32 s4, s47, s12
	global_load_lds_dwordx4 v[158:159], off
	v_lshl_add_u64 v[158:159], s[0:1], 0, v[140:141]
	s_mov_b32 m0, s4
	s_nop 0
	global_load_lds_dwordx4 v[158:159], off
	v_lshl_add_u64 v[158:159], s[0:1], 0, v[144:145]
	s_add_i32 m0, s4, 0x2000
	s_nop 0
	global_load_lds_dwordx4 v[158:159], off
	v_lshl_add_u64 v[158:159], v[238:239], 0, s[80:81]
	s_mov_b32 m0, s22
	s_nop 0
	global_load_lds_dwordx4 v[158:159], off
	v_lshl_add_u64 v[158:159], v[240:241], 0, s[80:81]
	s_mov_b32 m0, s23
	s_nop 0
	global_load_lds_dwordx4 v[158:159], off
	s_waitcnt vmcnt(8)
	s_waitcnt lgkmcnt(0)
	s_barrier
	s_setprio 1
	s_waitcnt lgkmcnt(0)
	v_mfma_f32_16x16x32_bf16 v[94:97], v[130:133], v[186:189], v[94:97]
	v_mfma_f32_16x16x32_bf16 v[30:33], v[150:153], v[186:189], v[30:33]
	v_mfma_f32_16x16x32_bf16 v[78:81], v[130:133], v[194:197], v[78:81]
	v_mfma_f32_16x16x32_bf16 v[18:21], v[150:153], v[194:197], v[18:21]
	v_mfma_f32_16x16x32_bf16 v[74:77], v[130:133], v[202:205], v[74:77]
	v_mfma_f32_16x16x32_bf16 v[10:13], v[150:153], v[202:205], v[10:13]
	v_mfma_f32_16x16x32_bf16 v[86:89], v[130:133], v[230:233], v[86:89]
	v_mfma_f32_16x16x32_bf16 v[22:25], v[150:153], v[230:233], v[22:25]
	v_mfma_f32_16x16x32_bf16 v[94:97], v[134:137], v[190:193], v[94:97]
	v_mfma_f32_16x16x32_bf16 v[30:33], v[154:157], v[190:193], v[30:33]
	v_mfma_f32_16x16x32_bf16 v[78:81], v[134:137], v[198:201], v[78:81]
	v_mfma_f32_16x16x32_bf16 v[18:21], v[154:157], v[198:201], v[18:21]
	v_mfma_f32_16x16x32_bf16 v[74:77], v[134:137], v[226:229], v[74:77]
	v_mfma_f32_16x16x32_bf16 v[10:13], v[154:157], v[226:229], v[10:13]
	v_mfma_f32_16x16x32_bf16 v[86:89], v[134:137], v[234:237], v[86:89]
	v_mfma_f32_16x16x32_bf16 v[22:25], v[154:157], v[234:237], v[22:25]
	s_setprio 0
	s_setprio 1
	v_mfma_f32_16x16x32_bf16 v[90:93], v[170:173], v[186:189], v[90:93]
	v_mfma_f32_16x16x32_bf16 v[26:29], v[178:181], v[186:189], v[26:29]
	v_mfma_f32_16x16x32_bf16 v[70:73], v[170:173], v[194:197], v[70:73]
	v_mfma_f32_16x16x32_bf16 v[6:9], v[178:181], v[194:197], v[6:9]
	v_mfma_f32_16x16x32_bf16 v[66:69], v[170:173], v[202:205], v[66:69]
	v_mfma_f32_16x16x32_bf16 v[2:5], v[178:181], v[202:205], v[2:5]
	v_mfma_f32_16x16x32_bf16 v[82:85], v[170:173], v[230:233], v[82:85]
	v_mfma_f32_16x16x32_bf16 v[14:17], v[178:181], v[230:233], v[14:17]
	v_mfma_f32_16x16x32_bf16 v[90:93], v[174:177], v[190:193], v[90:93]
	v_mfma_f32_16x16x32_bf16 v[26:29], v[182:185], v[190:193], v[26:29]
	v_mfma_f32_16x16x32_bf16 v[70:73], v[174:177], v[198:201], v[70:73]
	v_mfma_f32_16x16x32_bf16 v[6:9], v[182:185], v[198:201], v[6:9]
	v_mfma_f32_16x16x32_bf16 v[66:69], v[174:177], v[226:229], v[66:69]
	v_mfma_f32_16x16x32_bf16 v[2:5], v[182:185], v[226:229], v[2:5]
	v_mfma_f32_16x16x32_bf16 v[82:85], v[174:177], v[234:237], v[82:85]
	v_mfma_f32_16x16x32_bf16 v[14:17], v[182:185], v[234:237], v[14:17]
	s_setprio 0
	s_barrier
	s_add_i32 s35, s35, 2
	s_add_u32 s42, s42, 0x100
	s_addc_u32 s43, s43, 0
	s_add_u32 s29, s29, 0x100
	s_addc_u32 s34, s34, 0
	s_cmp_gt_u32 s35, 13

.LBB0_661:
	s_add_u32 s25, s0, 0x100
	s_addc_u32 s26, s1, 0
	s_mov_b32 s27, -2
	s_waitcnt lgkmcnt(0)
	s_mov_b64 s[60:61], 0x80
	s_waitcnt vmcnt(0)
	s_add_u32 s0, s56, 0x100
	s_addc_u32 s1, s57, 0
	s_add_i32 s28, 0, 0x10000
	s_cmp_eq_u32 s27, 40
	s_cselect_b32 s5, s45, s1
	s_cselect_b32 s4, s44, s0
	s_cselect_b32 s3, s55, s26
	s_cselect_b32 s2, s54, s25
	s_add_i32 s34, 0, 0x14000
	v_add_u32_e32 v126, s28, v189
	v_add_u32_e32 v178, s34, v189
	ds_read_b128 v[114:117], v126
	ds_read_b128 v[118:121], v126 offset:1024
	ds_read_b128 v[122:125], v126 offset:2048
	ds_read_b128 v[126:129], v126 offset:3072
	ds_read_b128 v[130:133], v178
	ds_read_b128 v[134:137], v178 offset:1024
	ds_read_b128 v[174:177], v178 offset:2048
	ds_read_b128 v[178:181], v178 offset:3072
	v_lshl_add_u64 v[186:187], s[56:57], 0, v[170:171]
	s_add_i32 m0, s14, 0xc000
	ds_read_b128 v[182:185], v191
	ds_read_b128 v[192:195], v191 offset:1024
	ds_read_b128 v[196:199], v191 offset:2048
	ds_read_b128 v[200:203], v191 offset:3072
	ds_read_b128 v[204:207], v191 offset:4096
	ds_read_b128 v[224:227], v191 offset:5120
	ds_read_b128 v[228:231], v191 offset:6144
	ds_read_b128 v[232:235], v191 offset:7168
	global_load_lds_dwordx4 v[186:187], off
	v_lshl_add_u64 v[186:187], s[56:57], 0, v[172:173]
	s_add_i32 m0, s14, 0xe000
	s_nop 0
	global_load_lds_dwordx4 v[186:187], off
	s_cmp_lg_u32 s27, -2
	s_cbranch_scc1 .Lpwt__662_0
	s_cmp_lt_u32 s20, 2
	s_cbranch_scc0 .Lpws__662_0

.Lpws__662_0:
	s_waitcnt lgkmcnt(0)
	s_barrier
	s_setprio 1
	s_waitcnt lgkmcnt(0)
	v_mfma_f32_16x16x32_bf16 v[150:153], v[114:117], v[182:185], 0
	v_mfma_f32_16x16x32_bf16 v[146:149], v[122:125], v[182:185], 0
	v_mfma_f32_16x16x32_bf16 v[110:113], v[114:117], v[196:199], 0
	v_mfma_f32_16x16x32_bf16 v[106:109], v[122:125], v[196:199], 0
	v_mfma_f32_16x16x32_bf16 v[94:97], v[114:117], v[204:207], 0
	v_mfma_f32_16x16x32_bf16 v[90:93], v[122:125], v[204:207], 0
	v_mfma_f32_16x16x32_bf16 v[78:81], v[114:117], v[228:231], 0
	v_mfma_f32_16x16x32_bf16 v[74:77], v[122:125], v[228:231], 0
	v_mfma_f32_16x16x32_bf16 v[150:153], v[118:121], v[192:195], v[150:153]
	v_mfma_f32_16x16x32_bf16 v[146:149], v[126:129], v[192:195], v[146:149]
	v_mfma_f32_16x16x32_bf16 v[110:113], v[118:121], v[200:203], v[110:113]
	v_mfma_f32_16x16x32_bf16 v[106:109], v[126:129], v[200:203], v[106:109]
	v_mfma_f32_16x16x32_bf16 v[94:97], v[118:121], v[224:227], v[94:97]
	v_mfma_f32_16x16x32_bf16 v[90:93], v[126:129], v[224:227], v[90:93]
	v_mfma_f32_16x16x32_bf16 v[78:81], v[118:121], v[232:235], v[78:81]
	v_mfma_f32_16x16x32_bf16 v[74:77], v[126:129], v[232:235], v[74:77]
	s_setprio 0
	s_setprio 1
	v_mfma_f32_16x16x32_bf16 v[142:145], v[130:133], v[182:185], 0
	v_mfma_f32_16x16x32_bf16 v[138:141], v[174:177], v[182:185], 0
	v_mfma_f32_16x16x32_bf16 v[102:105], v[130:133], v[196:199], 0
	v_mfma_f32_16x16x32_bf16 v[98:101], v[174:177], v[196:199], 0
	v_mfma_f32_16x16x32_bf16 v[86:89], v[130:133], v[204:207], 0
	v_mfma_f32_16x16x32_bf16 v[82:85], v[174:177], v[204:207], 0
	v_mfma_f32_16x16x32_bf16 v[70:73], v[130:133], v[228:231], 0
	v_mfma_f32_16x16x32_bf16 v[66:69], v[174:177], v[228:231], 0
	v_mfma_f32_16x16x32_bf16 v[142:145], v[134:137], v[192:195], v[142:145]
	v_mfma_f32_16x16x32_bf16 v[138:141], v[178:181], v[192:195], v[138:141]
	v_mfma_f32_16x16x32_bf16 v[102:105], v[134:137], v[200:203], v[102:105]
	v_mfma_f32_16x16x32_bf16 v[98:101], v[178:181], v[200:203], v[98:101]
	v_mfma_f32_16x16x32_bf16 v[86:89], v[134:137], v[224:227], v[86:89]
	v_mfma_f32_16x16x32_bf16 v[82:85], v[178:181], v[224:227], v[82:85]
	v_mfma_f32_16x16x32_bf16 v[70:73], v[134:137], v[232:235], v[70:73]
	v_mfma_f32_16x16x32_bf16 v[66:69], v[178:181], v[232:235], v[66:69]
	s_setprio 0
	s_barrier
	s_add_i32 s28, s28, s13
	v_lshl_add_u64 v[186:187], s[2:3], 0, v[0:1]
	s_mov_b32 m0, s28
	ds_read_b128 v[182:185], v191 offset:16384
	ds_read_b128 v[192:195], v191 offset:17408
	ds_read_b128 v[196:199], v191 offset:18432
	ds_read_b128 v[200:203], v191 offset:19456
	ds_read_b128 v[204:207], v191 offset:20480
	ds_read_b128 v[224:227], v191 offset:21504
	ds_read_b128 v[228:231], v191 offset:22528
	ds_read_b128 v[232:235], v191 offset:23552
	global_load_lds_dwordx4 v[186:187], off
	s_add_i32 m0, s28, 0x2000
	s_add_u32 s28, s2, 0xb0000
	v_lshl_add_u64 v[236:237], s[2:3], 0, v[158:159]
	s_addc_u32 s29, s3, 0
	s_add_i32 s34, s34, s13
	global_load_lds_dwordx4 v[236:237], off
	v_lshl_add_u64 v[238:239], s[28:29], 0, v[0:1]
	s_mov_b32 m0, s34
	v_lshl_add_u64 v[240:241], s[4:5], 0, v[156:157]
	global_load_lds_dwordx4 v[238:239], off
	v_lshl_add_u64 v[238:239], s[28:29], 0, v[158:159]
	s_add_i32 m0, s34, 0x2000
	s_nop 0
	global_load_lds_dwordx4 v[238:239], off
	v_lshl_add_u64 v[238:239], s[4:5], 0, v[154:155]
	s_mov_b32 m0, s14
	s_nop 0
	global_load_lds_dwordx4 v[238:239], off
	s_mov_b32 m0, s15
	s_nop 0
	global_load_lds_dwordx4 v[240:241], off
	s_cmp_lg_u32 s27, -2
	s_cbranch_scc1 .Lpwt__662_1
	s_cmp_lt_u32 s20, 2
	s_cbranch_scc0 .Lpws__662_1

.Lpws__662_1:
	s_waitcnt lgkmcnt(0)
	s_barrier
	s_setprio 1
	s_waitcnt lgkmcnt(0)
	v_mfma_f32_16x16x32_bf16 v[62:65], v[114:117], v[182:185], 0
	v_mfma_f32_16x16x32_bf16 v[58:61], v[122:125], v[182:185], 0
	v_mfma_f32_16x16x32_bf16 v[46:49], v[114:117], v[196:199], 0
	v_mfma_f32_16x16x32_bf16 v[42:45], v[122:125], v[196:199], 0
	v_mfma_f32_16x16x32_bf16 v[30:33], v[114:117], v[204:207], 0
	v_mfma_f32_16x16x32_bf16 v[26:29], v[122:125], v[204:207], 0
	v_mfma_f32_16x16x32_bf16 v[14:17], v[114:117], v[228:231], 0
	v_mfma_f32_16x16x32_bf16 v[10:13], v[122:125], v[228:231], 0
	v_mfma_f32_16x16x32_bf16 v[62:65], v[118:121], v[192:195], v[62:65]
	v_mfma_f32_16x16x32_bf16 v[58:61], v[126:129], v[192:195], v[58:61]
	v_mfma_f32_16x16x32_bf16 v[46:49], v[118:121], v[200:203], v[46:49]
	v_mfma_f32_16x16x32_bf16 v[42:45], v[126:129], v[200:203], v[42:45]
	v_mfma_f32_16x16x32_bf16 v[30:33], v[118:121], v[224:227], v[30:33]
	v_mfma_f32_16x16x32_bf16 v[26:29], v[126:129], v[224:227], v[26:29]
	v_mfma_f32_16x16x32_bf16 v[14:17], v[118:121], v[232:235], v[14:17]
	v_mfma_f32_16x16x32_bf16 v[10:13], v[126:129], v[232:235], v[10:13]
	s_setprio 0
	s_setprio 1
	v_mfma_f32_16x16x32_bf16 v[54:57], v[130:133], v[182:185], 0
	v_mfma_f32_16x16x32_bf16 v[50:53], v[174:177], v[182:185], 0
	v_mfma_f32_16x16x32_bf16 v[38:41], v[130:133], v[196:199], 0
	v_mfma_f32_16x16x32_bf16 v[34:37], v[174:177], v[196:199], 0
	v_mfma_f32_16x16x32_bf16 v[22:25], v[130:133], v[204:207], 0
	v_mfma_f32_16x16x32_bf16 v[18:21], v[174:177], v[204:207], 0
	v_mfma_f32_16x16x32_bf16 v[6:9], v[130:133], v[228:231], 0
	v_mfma_f32_16x16x32_bf16 v[2:5], v[174:177], v[228:231], 0
	v_mfma_f32_16x16x32_bf16 v[54:57], v[134:137], v[192:195], v[54:57]
	v_mfma_f32_16x16x32_bf16 v[50:53], v[178:181], v[192:195], v[50:53]
	v_mfma_f32_16x16x32_bf16 v[38:41], v[134:137], v[200:203], v[38:41]
	v_mfma_f32_16x16x32_bf16 v[34:37], v[178:181], v[200:203], v[34:37]
	v_mfma_f32_16x16x32_bf16 v[22:25], v[134:137], v[224:227], v[22:25]
	v_mfma_f32_16x16x32_bf16 v[18:21], v[178:181], v[224:227], v[18:21]
	v_mfma_f32_16x16x32_bf16 v[6:9], v[134:137], v[232:235], v[6:9]
	v_mfma_f32_16x16x32_bf16 v[2:5], v[178:181], v[232:235], v[2:5]
	s_setprio 0
	s_barrier
	s_add_i32 s28, 0, 0x18000
	s_add_i32 s29, 0, 0x1c000
	v_add_u32_e32 v126, s28, v189
	v_add_u32_e32 v178, s29, v189
	ds_read_b128 v[114:117], v126
	ds_read_b128 v[118:121], v126 offset:1024
	ds_read_b128 v[122:125], v126 offset:2048
	ds_read_b128 v[126:129], v126 offset:3072
	ds_read_b128 v[130:133], v178
	ds_read_b128 v[134:137], v178 offset:1024
	ds_read_b128 v[174:177], v178 offset:2048
	ds_read_b128 v[178:181], v178 offset:3072
	s_add_u32 s4, s4, 0xb0000
	s_addc_u32 s5, s5, 0
	s_mov_b32 m0, s16
	v_lshl_add_u64 v[242:243], s[4:5], 0, v[154:155]
	ds_read_b128 v[182:185], v191 offset:32768
	ds_read_b128 v[192:195], v191 offset:33792
	ds_read_b128 v[196:199], v191 offset:34816
	ds_read_b128 v[200:203], v191 offset:35840
	ds_read_b128 v[204:207], v191 offset:36864
	ds_read_b128 v[224:227], v191 offset:37888
	ds_read_b128 v[228:231], v191 offset:38912
	ds_read_b128 v[232:235], v191 offset:39936
	global_load_lds_dwordx4 v[242:243], off
	v_lshl_add_u64 v[242:243], s[4:5], 0, v[156:157]
	s_mov_b32 m0, s17
	s_nop 0
	global_load_lds_dwordx4 v[242:243], off
	s_waitcnt vmcnt(8)
	s_waitcnt lgkmcnt(0)
	s_barrier
	s_setprio 1
	s_waitcnt lgkmcnt(0)
	v_mfma_f32_16x16x32_bf16 v[150:153], v[114:117], v[182:185], v[150:153]
	v_mfma_f32_16x16x32_bf16 v[146:149], v[122:125], v[182:185], v[146:149]
	v_mfma_f32_16x16x32_bf16 v[110:113], v[114:117], v[196:199], v[110:113]
	v_mfma_f32_16x16x32_bf16 v[106:109], v[122:125], v[196:199], v[106:109]
	v_mfma_f32_16x16x32_bf16 v[94:97], v[114:117], v[204:207], v[94:97]
	v_mfma_f32_16x16x32_bf16 v[90:93], v[122:125], v[204:207], v[90:93]
	v_mfma_f32_16x16x32_bf16 v[78:81], v[114:117], v[228:231], v[78:81]
	v_mfma_f32_16x16x32_bf16 v[74:77], v[122:125], v[228:231], v[74:77]
	v_mfma_f32_16x16x32_bf16 v[150:153], v[118:121], v[192:195], v[150:153]
	v_mfma_f32_16x16x32_bf16 v[146:149], v[126:129], v[192:195], v[146:149]
	v_mfma_f32_16x16x32_bf16 v[110:113], v[118:121], v[200:203], v[110:113]
	v_mfma_f32_16x16x32_bf16 v[106:109], v[126:129], v[200:203], v[106:109]
	v_mfma_f32_16x16x32_bf16 v[94:97], v[118:121], v[224:227], v[94:97]
	v_mfma_f32_16x16x32_bf16 v[90:93], v[126:129], v[224:227], v[90:93]
	v_mfma_f32_16x16x32_bf16 v[78:81], v[118:121], v[232:235], v[78:81]
	v_mfma_f32_16x16x32_bf16 v[74:77], v[126:129], v[232:235], v[74:77]
	s_setprio 0
	s_setprio 1
	v_mfma_f32_16x16x32_bf16 v[142:145], v[130:133], v[182:185], v[142:145]
	v_mfma_f32_16x16x32_bf16 v[138:141], v[174:177], v[182:185], v[138:141]
	v_mfma_f32_16x16x32_bf16 v[102:105], v[130:133], v[196:199], v[102:105]
	v_mfma_f32_16x16x32_bf16 v[98:101], v[174:177], v[196:199], v[98:101]
	v_mfma_f32_16x16x32_bf16 v[86:89], v[130:133], v[204:207], v[86:89]
	v_mfma_f32_16x16x32_bf16 v[82:85], v[174:177], v[204:207], v[82:85]
	v_mfma_f32_16x16x32_bf16 v[70:73], v[130:133], v[228:231], v[70:73]
	v_mfma_f32_16x16x32_bf16 v[66:69], v[174:177], v[228:231], v[66:69]
	v_mfma_f32_16x16x32_bf16 v[142:145], v[134:137], v[192:195], v[142:145]
	v_mfma_f32_16x16x32_bf16 v[138:141], v[178:181], v[192:195], v[138:141]
	v_mfma_f32_16x16x32_bf16 v[102:105], v[134:137], v[200:203], v[102:105]
	v_mfma_f32_16x16x32_bf16 v[98:101], v[178:181], v[200:203], v[98:101]
	v_mfma_f32_16x16x32_bf16 v[86:89], v[134:137], v[224:227], v[86:89]
	v_mfma_f32_16x16x32_bf16 v[82:85], v[178:181], v[224:227], v[82:85]
	v_mfma_f32_16x16x32_bf16 v[70:73], v[134:137], v[232:235], v[70:73]
	v_mfma_f32_16x16x32_bf16 v[66:69], v[178:181], v[232:235], v[66:69]
	s_setprio 0
	s_barrier
	s_add_i32 s4, s28, s13
	v_lshl_add_u64 v[186:187], v[186:187], 0, s[60:61]
	s_mov_b32 m0, s4
	ds_read_b128 v[182:185], v191 offset:49152
	ds_read_b128 v[192:195], v191 offset:50176
	ds_read_b128 v[196:199], v191 offset:51200
	ds_read_b128 v[200:203], v191 offset:52224
	ds_read_b128 v[204:207], v191 offset:53248
	ds_read_b128 v[224:227], v191 offset:54272
	ds_read_b128 v[228:231], v191 offset:55296
	ds_read_b128 v[232:235], v191 offset:56320
	global_load_lds_dwordx4 v[186:187], off
	s_add_i32 m0, s4, 0x2000
	s_add_u32 s2, s2, 0xb0080
	v_lshl_add_u64 v[186:187], v[236:237], 0, s[60:61]
	s_addc_u32 s3, s3, 0
	s_add_i32 s4, s29, s13
	global_load_lds_dwordx4 v[186:187], off
	v_lshl_add_u64 v[186:187], s[2:3], 0, v[0:1]
	s_mov_b32 m0, s4
	s_nop 0
	global_load_lds_dwordx4 v[186:187], off
	v_lshl_add_u64 v[186:187], s[2:3], 0, v[158:159]
	s_add_i32 m0, s4, 0x2000
	s_nop 0
	global_load_lds_dwordx4 v[186:187], off
	v_lshl_add_u64 v[186:187], v[238:239], 0, s[60:61]
	s_mov_b32 m0, s18
	s_nop 0
	global_load_lds_dwordx4 v[186:187], off
	v_lshl_add_u64 v[186:187], v[240:241], 0, s[60:61]
	s_mov_b32 m0, s19
	s_nop 0
	global_load_lds_dwordx4 v[186:187], off
	s_waitcnt vmcnt(8)
	s_waitcnt lgkmcnt(0)
	s_barrier
	s_setprio 1
	s_waitcnt lgkmcnt(0)
	v_mfma_f32_16x16x32_bf16 v[62:65], v[114:117], v[182:185], v[62:65]
	v_mfma_f32_16x16x32_bf16 v[58:61], v[122:125], v[182:185], v[58:61]
	v_mfma_f32_16x16x32_bf16 v[46:49], v[114:117], v[196:199], v[46:49]
	v_mfma_f32_16x16x32_bf16 v[42:45], v[122:125], v[196:199], v[42:45]
	v_mfma_f32_16x16x32_bf16 v[30:33], v[114:117], v[204:207], v[30:33]
	v_mfma_f32_16x16x32_bf16 v[26:29], v[122:125], v[204:207], v[26:29]
	v_mfma_f32_16x16x32_bf16 v[14:17], v[114:117], v[228:231], v[14:17]
	v_mfma_f32_16x16x32_bf16 v[10:13], v[122:125], v[228:231], v[10:13]
	v_mfma_f32_16x16x32_bf16 v[62:65], v[118:121], v[192:195], v[62:65]
	v_mfma_f32_16x16x32_bf16 v[58:61], v[126:129], v[192:195], v[58:61]
	v_mfma_f32_16x16x32_bf16 v[46:49], v[118:121], v[200:203], v[46:49]
	v_mfma_f32_16x16x32_bf16 v[42:45], v[126:129], v[200:203], v[42:45]
	v_mfma_f32_16x16x32_bf16 v[30:33], v[118:121], v[224:227], v[30:33]
	v_mfma_f32_16x16x32_bf16 v[26:29], v[126:129], v[224:227], v[26:29]
	v_mfma_f32_16x16x32_bf16 v[14:17], v[118:121], v[232:235], v[14:17]
	v_mfma_f32_16x16x32_bf16 v[10:13], v[126:129], v[232:235], v[10:13]
	s_setprio 0
	s_setprio 1
	v_mfma_f32_16x16x32_bf16 v[54:57], v[130:133], v[182:185], v[54:57]
	v_mfma_f32_16x16x32_bf16 v[50:53], v[174:177], v[182:185], v[50:53]
	v_mfma_f32_16x16x32_bf16 v[38:41], v[130:133], v[196:199], v[38:41]
	v_mfma_f32_16x16x32_bf16 v[34:37], v[174:177], v[196:199], v[34:37]
	v_mfma_f32_16x16x32_bf16 v[22:25], v[130:133], v[204:207], v[22:25]
	v_mfma_f32_16x16x32_bf16 v[18:21], v[174:177], v[204:207], v[18:21]
	v_mfma_f32_16x16x32_bf16 v[6:9], v[130:133], v[228:231], v[6:9]
	v_mfma_f32_16x16x32_bf16 v[2:5], v[174:177], v[228:231], v[2:5]
	v_mfma_f32_16x16x32_bf16 v[54:57], v[134:137], v[192:195], v[54:57]
	v_mfma_f32_16x16x32_bf16 v[50:53], v[178:181], v[192:195], v[50:53]
	v_mfma_f32_16x16x32_bf16 v[38:41], v[134:137], v[200:203], v[38:41]
	v_mfma_f32_16x16x32_bf16 v[34:37], v[178:181], v[200:203], v[34:37]
	v_mfma_f32_16x16x32_bf16 v[22:25], v[134:137], v[224:227], v[22:25]
	v_mfma_f32_16x16x32_bf16 v[18:21], v[178:181], v[224:227], v[18:21]
	v_mfma_f32_16x16x32_bf16 v[6:9], v[134:137], v[232:235], v[6:9]
	v_mfma_f32_16x16x32_bf16 v[2:5], v[178:181], v[232:235], v[2:5]
	s_setprio 0
	s_barrier
	s_add_i32 s27, s27, 2
	s_add_u32 s25, s25, 0x100
	s_addc_u32 s26, s26, 0
	s_cmp_gt_u32 s27, 41
	s_mov_b64 s[56:57], s[0:1]

.LBB0_777:
	s_ashr_i32 s45, s44, 31
	s_lshl_b64 s[4:5], s[44:45], 19
	s_add_u32 s4, s10, s4
	s_addc_u32 s5, s11, s5
	s_and_b64 s[24:25], s[40:41], exec
	s_cselect_b32 s23, s5, s7
	s_cselect_b32 s24, s4, s6
	s_ashr_i32 s39, s38, 31
	s_lshl_b64 s[28:29], s[38:39], 19
	v_readlane_b32 s34, v254, 43
	v_readlane_b32 s35, v254, 44
	s_add_u32 s48, s34, s28
	s_addc_u32 s49, s35, s29
	s_and_b64 s[28:29], s[40:41], exec
	s_cselect_b32 s25, s49, s1
	s_cselect_b32 s28, s48, s0
	s_add_u32 s42, s6, 0x40080
	s_addc_u32 s43, s7, 0
	s_add_u32 s29, s0, 0x100
	s_addc_u32 s34, s1, 0
	s_mov_b32 s35, -2
	s_mov_b64 s[56:57], 0x80
	s_add_u32 s0, s42, 0xfffc0080
	s_addc_u32 s1, s43, -1
	s_add_i32 s39, 0, 0x10000
	s_cmp_eq_u32 s35, 12
	s_cselect_b32 s7, s23, s1
	s_cselect_b32 s6, s24, s0
	s_cselect_b32 s1, s25, s34
	s_cselect_b32 s0, s28, s29
	s_add_i32 s45, 0, 0x14000
	v_add_u32_e32 v142, s39, v179
	v_add_u32_e32 v182, s45, v179
	ds_read_b128 v[130:133], v142
	ds_read_b128 v[134:137], v142 offset:1024
	ds_read_b128 v[138:141], v142 offset:2048
	ds_read_b128 v[142:145], v142 offset:3072
	ds_read_b128 v[156:159], v182
	ds_read_b128 v[170:173], v182 offset:1024
	ds_read_b128 v[174:177], v182 offset:2048
	ds_read_b128 v[182:185], v182 offset:3072
	v_lshl_add_u64 v[206:207], s[42:43], 0, v[152:153]
	s_add_i32 m0, s14, 0xc000
	ds_read_b128 v[186:189], v181
	ds_read_b128 v[190:193], v181 offset:1024
	ds_read_b128 v[194:197], v181 offset:2048
	ds_read_b128 v[198:201], v181 offset:3072
	ds_read_b128 v[202:205], v181 offset:4096
	ds_read_b128 v[224:227], v181 offset:5120
	ds_read_b128 v[228:231], v181 offset:6144
	ds_read_b128 v[232:235], v181 offset:7168
	global_load_lds_dwordx4 v[206:207], off
	v_lshl_add_u64 v[206:207], s[42:43], 0, v[154:155]
	s_add_i32 m0, s14, 0xe000
	s_nop 0
	global_load_lds_dwordx4 v[206:207], off
	s_cmp_lg_u32 s35, -2
	s_cbranch_scc1 .Lpwt__778_0
	s_cmp_lt_u32 s21, 2
	s_cbranch_scc0 .Lpws__778_0

.Lpws__778_0:
	s_waitcnt lgkmcnt(0)
	s_barrier
	s_setprio 1
	s_waitcnt lgkmcnt(0)
	v_mfma_f32_16x16x32_bf16 v[126:129], v[130:133], v[186:189], 0
	v_mfma_f32_16x16x32_bf16 v[122:125], v[138:141], v[186:189], 0
	v_mfma_f32_16x16x32_bf16 v[114:117], v[130:133], v[194:197], 0
	v_mfma_f32_16x16x32_bf16 v[106:109], v[138:141], v[194:197], 0
	v_mfma_f32_16x16x32_bf16 v[98:101], v[130:133], v[202:205], 0
	v_mfma_f32_16x16x32_bf16 v[90:93], v[138:141], v[202:205], 0
	v_mfma_f32_16x16x32_bf16 v[82:85], v[130:133], v[228:231], 0
	v_mfma_f32_16x16x32_bf16 v[74:77], v[138:141], v[228:231], 0
	v_mfma_f32_16x16x32_bf16 v[126:129], v[134:137], v[190:193], v[126:129]
	v_mfma_f32_16x16x32_bf16 v[122:125], v[142:145], v[190:193], v[122:125]
	v_mfma_f32_16x16x32_bf16 v[114:117], v[134:137], v[198:201], v[114:117]
	v_mfma_f32_16x16x32_bf16 v[106:109], v[142:145], v[198:201], v[106:109]
	v_mfma_f32_16x16x32_bf16 v[98:101], v[134:137], v[224:227], v[98:101]
	v_mfma_f32_16x16x32_bf16 v[90:93], v[142:145], v[224:227], v[90:93]
	v_mfma_f32_16x16x32_bf16 v[82:85], v[134:137], v[232:235], v[82:85]
	v_mfma_f32_16x16x32_bf16 v[74:77], v[142:145], v[232:235], v[74:77]
	s_setprio 0
	s_setprio 1
	v_mfma_f32_16x16x32_bf16 v[118:121], v[156:159], v[186:189], 0
	v_mfma_f32_16x16x32_bf16 v[110:113], v[174:177], v[186:189], 0
	v_mfma_f32_16x16x32_bf16 v[102:105], v[156:159], v[194:197], 0
	v_mfma_f32_16x16x32_bf16 v[94:97], v[174:177], v[194:197], 0
	v_mfma_f32_16x16x32_bf16 v[86:89], v[156:159], v[202:205], 0
	v_mfma_f32_16x16x32_bf16 v[78:81], v[174:177], v[202:205], 0
	v_mfma_f32_16x16x32_bf16 v[70:73], v[156:159], v[228:231], 0
	v_mfma_f32_16x16x32_bf16 v[66:69], v[174:177], v[228:231], 0
	v_mfma_f32_16x16x32_bf16 v[118:121], v[170:173], v[190:193], v[118:121]
	v_mfma_f32_16x16x32_bf16 v[110:113], v[182:185], v[190:193], v[110:113]
	v_mfma_f32_16x16x32_bf16 v[102:105], v[170:173], v[198:201], v[102:105]
	v_mfma_f32_16x16x32_bf16 v[94:97], v[182:185], v[198:201], v[94:97]
	v_mfma_f32_16x16x32_bf16 v[86:89], v[170:173], v[224:227], v[86:89]
	v_mfma_f32_16x16x32_bf16 v[78:81], v[182:185], v[224:227], v[78:81]
	v_mfma_f32_16x16x32_bf16 v[70:73], v[170:173], v[232:235], v[70:73]
	v_mfma_f32_16x16x32_bf16 v[66:69], v[182:185], v[232:235], v[66:69]
	s_setprio 0
	s_barrier
	s_add_i32 s39, s39, s12
	v_lshl_add_u64 v[206:207], s[0:1], 0, v[0:1]
	s_mov_b32 m0, s39
	ds_read_b128 v[186:189], v181 offset:16384
	ds_read_b128 v[190:193], v181 offset:17408
	ds_read_b128 v[194:197], v181 offset:18432
	ds_read_b128 v[198:201], v181 offset:19456
	ds_read_b128 v[202:205], v181 offset:20480
	ds_read_b128 v[224:227], v181 offset:21504
	ds_read_b128 v[228:231], v181 offset:22528
	ds_read_b128 v[232:235], v181 offset:23552
	global_load_lds_dwordx4 v[206:207], off
	s_add_i32 m0, s39, 0x2000
	s_add_u32 s46, s0, 0x40000
	v_lshl_add_u64 v[236:237], s[0:1], 0, v[146:147]
	s_addc_u32 s47, s1, 0
	s_add_i32 s39, s45, s12
	global_load_lds_dwordx4 v[236:237], off
	v_lshl_add_u64 v[238:239], s[46:47], 0, v[0:1]
	s_mov_b32 m0, s39
	v_lshl_add_u64 v[240:241], s[6:7], 0, v[148:149]
	global_load_lds_dwordx4 v[238:239], off
	v_lshl_add_u64 v[238:239], s[46:47], 0, v[146:147]
	s_add_i32 m0, s39, 0x2000
	s_nop 0
	global_load_lds_dwordx4 v[238:239], off
	v_lshl_add_u64 v[238:239], s[6:7], 0, v[150:151]
	s_mov_b32 m0, s14
	s_nop 0
	global_load_lds_dwordx4 v[238:239], off
	s_mov_b32 m0, s15
	s_nop 0
	global_load_lds_dwordx4 v[240:241], off
	s_cmp_lg_u32 s35, -2
	s_cbranch_scc1 .Lpwt__778_1
	s_cmp_lt_u32 s21, 2
	s_cbranch_scc0 .Lpws__778_1

.Lpws__778_1:
	s_waitcnt lgkmcnt(0)
	s_barrier
	s_setprio 1
	s_waitcnt lgkmcnt(0)
	v_mfma_f32_16x16x32_bf16 v[62:65], v[130:133], v[186:189], 0
	v_mfma_f32_16x16x32_bf16 v[58:61], v[138:141], v[186:189], 0
	v_mfma_f32_16x16x32_bf16 v[50:53], v[130:133], v[194:197], 0
	v_mfma_f32_16x16x32_bf16 v[42:45], v[138:141], v[194:197], 0
	v_mfma_f32_16x16x32_bf16 v[34:37], v[130:133], v[202:205], 0
	v_mfma_f32_16x16x32_bf16 v[26:29], v[138:141], v[202:205], 0
	v_mfma_f32_16x16x32_bf16 v[18:21], v[130:133], v[228:231], 0
	v_mfma_f32_16x16x32_bf16 v[10:13], v[138:141], v[228:231], 0
	v_mfma_f32_16x16x32_bf16 v[62:65], v[134:137], v[190:193], v[62:65]
	v_mfma_f32_16x16x32_bf16 v[58:61], v[142:145], v[190:193], v[58:61]
	v_mfma_f32_16x16x32_bf16 v[50:53], v[134:137], v[198:201], v[50:53]
	v_mfma_f32_16x16x32_bf16 v[42:45], v[142:145], v[198:201], v[42:45]
	v_mfma_f32_16x16x32_bf16 v[34:37], v[134:137], v[224:227], v[34:37]
	v_mfma_f32_16x16x32_bf16 v[26:29], v[142:145], v[224:227], v[26:29]
	v_mfma_f32_16x16x32_bf16 v[18:21], v[134:137], v[232:235], v[18:21]
	v_mfma_f32_16x16x32_bf16 v[10:13], v[142:145], v[232:235], v[10:13]
	s_setprio 0
	s_setprio 1
	v_mfma_f32_16x16x32_bf16 v[54:57], v[156:159], v[186:189], 0
	v_mfma_f32_16x16x32_bf16 v[46:49], v[174:177], v[186:189], 0
	v_mfma_f32_16x16x32_bf16 v[38:41], v[156:159], v[194:197], 0
	v_mfma_f32_16x16x32_bf16 v[30:33], v[174:177], v[194:197], 0
	v_mfma_f32_16x16x32_bf16 v[22:25], v[156:159], v[202:205], 0
	v_mfma_f32_16x16x32_bf16 v[14:17], v[174:177], v[202:205], 0
	v_mfma_f32_16x16x32_bf16 v[6:9], v[156:159], v[228:231], 0
	v_mfma_f32_16x16x32_bf16 v[2:5], v[174:177], v[228:231], 0
	v_mfma_f32_16x16x32_bf16 v[54:57], v[170:173], v[190:193], v[54:57]
	v_mfma_f32_16x16x32_bf16 v[46:49], v[182:185], v[190:193], v[46:49]
	v_mfma_f32_16x16x32_bf16 v[38:41], v[170:173], v[198:201], v[38:41]
	v_mfma_f32_16x16x32_bf16 v[30:33], v[182:185], v[198:201], v[30:33]
	v_mfma_f32_16x16x32_bf16 v[22:25], v[170:173], v[224:227], v[22:25]
	v_mfma_f32_16x16x32_bf16 v[14:17], v[182:185], v[224:227], v[14:17]
	v_mfma_f32_16x16x32_bf16 v[6:9], v[170:173], v[232:235], v[6:9]
	v_mfma_f32_16x16x32_bf16 v[2:5], v[182:185], v[232:235], v[2:5]
	s_setprio 0
	s_barrier
	s_add_i32 s39, 0, 0x18000
	s_add_i32 s45, 0, 0x1c000
	v_add_u32_e32 v142, s39, v179
	v_add_u32_e32 v182, s45, v179
	ds_read_b128 v[130:133], v142
	ds_read_b128 v[134:137], v142 offset:1024
	ds_read_b128 v[138:141], v142 offset:2048
	ds_read_b128 v[142:145], v142 offset:3072
	ds_read_b128 v[156:159], v182
	ds_read_b128 v[170:173], v182 offset:1024
	ds_read_b128 v[174:177], v182 offset:2048
	ds_read_b128 v[182:185], v182 offset:3072
	s_add_u32 s6, s6, 0x40000
	s_addc_u32 s7, s7, 0
	s_mov_b32 m0, s16
	v_lshl_add_u64 v[242:243], s[6:7], 0, v[150:151]
	ds_read_b128 v[186:189], v181 offset:32768
	ds_read_b128 v[190:193], v181 offset:33792
	ds_read_b128 v[194:197], v181 offset:34816
	ds_read_b128 v[198:201], v181 offset:35840
	ds_read_b128 v[202:205], v181 offset:36864
	ds_read_b128 v[224:227], v181 offset:37888
	ds_read_b128 v[228:231], v181 offset:38912
	ds_read_b128 v[232:235], v181 offset:39936
	global_load_lds_dwordx4 v[242:243], off
	v_lshl_add_u64 v[242:243], s[6:7], 0, v[148:149]
	s_mov_b32 m0, s17
	s_nop 0
	global_load_lds_dwordx4 v[242:243], off
	s_waitcnt vmcnt(8)
	s_waitcnt lgkmcnt(0)
	s_barrier
	s_setprio 1
	s_waitcnt lgkmcnt(0)
	v_mfma_f32_16x16x32_bf16 v[126:129], v[130:133], v[186:189], v[126:129]
	v_mfma_f32_16x16x32_bf16 v[122:125], v[138:141], v[186:189], v[122:125]
	v_mfma_f32_16x16x32_bf16 v[114:117], v[130:133], v[194:197], v[114:117]
	v_mfma_f32_16x16x32_bf16 v[106:109], v[138:141], v[194:197], v[106:109]
	v_mfma_f32_16x16x32_bf16 v[98:101], v[130:133], v[202:205], v[98:101]
	v_mfma_f32_16x16x32_bf16 v[90:93], v[138:141], v[202:205], v[90:93]
	v_mfma_f32_16x16x32_bf16 v[82:85], v[130:133], v[228:231], v[82:85]
	v_mfma_f32_16x16x32_bf16 v[74:77], v[138:141], v[228:231], v[74:77]
	v_mfma_f32_16x16x32_bf16 v[126:129], v[134:137], v[190:193], v[126:129]
	v_mfma_f32_16x16x32_bf16 v[122:125], v[142:145], v[190:193], v[122:125]
	v_mfma_f32_16x16x32_bf16 v[114:117], v[134:137], v[198:201], v[114:117]
	v_mfma_f32_16x16x32_bf16 v[106:109], v[142:145], v[198:201], v[106:109]
	v_mfma_f32_16x16x32_bf16 v[98:101], v[134:137], v[224:227], v[98:101]
	v_mfma_f32_16x16x32_bf16 v[90:93], v[142:145], v[224:227], v[90:93]
	v_mfma_f32_16x16x32_bf16 v[82:85], v[134:137], v[232:235], v[82:85]
	v_mfma_f32_16x16x32_bf16 v[74:77], v[142:145], v[232:235], v[74:77]
	s_setprio 0
	s_setprio 1
	v_mfma_f32_16x16x32_bf16 v[118:121], v[156:159], v[186:189], v[118:121]
	v_mfma_f32_16x16x32_bf16 v[110:113], v[174:177], v[186:189], v[110:113]
	v_mfma_f32_16x16x32_bf16 v[102:105], v[156:159], v[194:197], v[102:105]
	v_mfma_f32_16x16x32_bf16 v[94:97], v[174:177], v[194:197], v[94:97]
	v_mfma_f32_16x16x32_bf16 v[86:89], v[156:159], v[202:205], v[86:89]
	v_mfma_f32_16x16x32_bf16 v[78:81], v[174:177], v[202:205], v[78:81]
	v_mfma_f32_16x16x32_bf16 v[70:73], v[156:159], v[228:231], v[70:73]
	v_mfma_f32_16x16x32_bf16 v[66:69], v[174:177], v[228:231], v[66:69]
	v_mfma_f32_16x16x32_bf16 v[118:121], v[170:173], v[190:193], v[118:121]
	v_mfma_f32_16x16x32_bf16 v[110:113], v[182:185], v[190:193], v[110:113]
	v_mfma_f32_16x16x32_bf16 v[102:105], v[170:173], v[198:201], v[102:105]
	v_mfma_f32_16x16x32_bf16 v[94:97], v[182:185], v[198:201], v[94:97]
	v_mfma_f32_16x16x32_bf16 v[86:89], v[170:173], v[224:227], v[86:89]
	v_mfma_f32_16x16x32_bf16 v[78:81], v[182:185], v[224:227], v[78:81]
	v_mfma_f32_16x16x32_bf16 v[70:73], v[170:173], v[232:235], v[70:73]
	v_mfma_f32_16x16x32_bf16 v[66:69], v[182:185], v[232:235], v[66:69]
	s_setprio 0
	s_barrier
	s_add_i32 s6, s39, s12
	v_lshl_add_u64 v[206:207], v[206:207], 0, s[56:57]
	s_mov_b32 m0, s6
	ds_read_b128 v[186:189], v181 offset:49152
	ds_read_b128 v[190:193], v181 offset:50176
	ds_read_b128 v[194:197], v181 offset:51200
	ds_read_b128 v[198:201], v181 offset:52224
	ds_read_b128 v[202:205], v181 offset:53248
	ds_read_b128 v[224:227], v181 offset:54272
	ds_read_b128 v[228:231], v181 offset:55296
	ds_read_b128 v[232:235], v181 offset:56320
	global_load_lds_dwordx4 v[206:207], off
	s_add_i32 m0, s6, 0x2000
	s_add_u32 s0, s0, 0x40080
	v_lshl_add_u64 v[206:207], v[236:237], 0, s[56:57]
	s_addc_u32 s1, s1, 0
	s_add_i32 s6, s45, s12
	global_load_lds_dwordx4 v[206:207], off
	v_lshl_add_u64 v[206:207], s[0:1], 0, v[0:1]
	s_mov_b32 m0, s6
	s_nop 0
	global_load_lds_dwordx4 v[206:207], off
	v_lshl_add_u64 v[206:207], s[0:1], 0, v[146:147]
	s_add_i32 m0, s6, 0x2000
	s_nop 0
	global_load_lds_dwordx4 v[206:207], off
	v_lshl_add_u64 v[206:207], v[238:239], 0, s[56:57]
	s_mov_b32 m0, s18
	s_nop 0
	global_load_lds_dwordx4 v[206:207], off
	v_lshl_add_u64 v[206:207], v[240:241], 0, s[56:57]
	s_mov_b32 m0, s19
	s_nop 0
	global_load_lds_dwordx4 v[206:207], off
	s_waitcnt vmcnt(8)
	s_waitcnt lgkmcnt(0)
	s_barrier
	s_setprio 1
	s_waitcnt lgkmcnt(0)
	v_mfma_f32_16x16x32_bf16 v[62:65], v[130:133], v[186:189], v[62:65]
	v_mfma_f32_16x16x32_bf16 v[58:61], v[138:141], v[186:189], v[58:61]
	v_mfma_f32_16x16x32_bf16 v[50:53], v[130:133], v[194:197], v[50:53]
	v_mfma_f32_16x16x32_bf16 v[42:45], v[138:141], v[194:197], v[42:45]
	v_mfma_f32_16x16x32_bf16 v[34:37], v[130:133], v[202:205], v[34:37]
	v_mfma_f32_16x16x32_bf16 v[26:29], v[138:141], v[202:205], v[26:29]
	v_mfma_f32_16x16x32_bf16 v[18:21], v[130:133], v[228:231], v[18:21]
	v_mfma_f32_16x16x32_bf16 v[10:13], v[138:141], v[228:231], v[10:13]
	v_mfma_f32_16x16x32_bf16 v[62:65], v[134:137], v[190:193], v[62:65]
	v_mfma_f32_16x16x32_bf16 v[58:61], v[142:145], v[190:193], v[58:61]
	v_mfma_f32_16x16x32_bf16 v[50:53], v[134:137], v[198:201], v[50:53]
	v_mfma_f32_16x16x32_bf16 v[42:45], v[142:145], v[198:201], v[42:45]
	v_mfma_f32_16x16x32_bf16 v[34:37], v[134:137], v[224:227], v[34:37]
	v_mfma_f32_16x16x32_bf16 v[26:29], v[142:145], v[224:227], v[26:29]
	v_mfma_f32_16x16x32_bf16 v[18:21], v[134:137], v[232:235], v[18:21]
	v_mfma_f32_16x16x32_bf16 v[10:13], v[142:145], v[232:235], v[10:13]
	s_setprio 0
	s_setprio 1
	v_mfma_f32_16x16x32_bf16 v[54:57], v[156:159], v[186:189], v[54:57]
	v_mfma_f32_16x16x32_bf16 v[46:49], v[174:177], v[186:189], v[46:49]
	v_mfma_f32_16x16x32_bf16 v[38:41], v[156:159], v[194:197], v[38:41]
	v_mfma_f32_16x16x32_bf16 v[30:33], v[174:177], v[194:197], v[30:33]
	v_mfma_f32_16x16x32_bf16 v[22:25], v[156:159], v[202:205], v[22:25]
	v_mfma_f32_16x16x32_bf16 v[14:17], v[174:177], v[202:205], v[14:17]
	v_mfma_f32_16x16x32_bf16 v[6:9], v[156:159], v[228:231], v[6:9]
	v_mfma_f32_16x16x32_bf16 v[2:5], v[174:177], v[228:231], v[2:5]
	v_mfma_f32_16x16x32_bf16 v[54:57], v[170:173], v[190:193], v[54:57]
	v_mfma_f32_16x16x32_bf16 v[46:49], v[182:185], v[190:193], v[46:49]
	v_mfma_f32_16x16x32_bf16 v[38:41], v[170:173], v[198:201], v[38:41]
	v_mfma_f32_16x16x32_bf16 v[30:33], v[182:185], v[198:201], v[30:33]
	v_mfma_f32_16x16x32_bf16 v[22:25], v[170:173], v[224:227], v[22:25]
	v_mfma_f32_16x16x32_bf16 v[14:17], v[182:185], v[224:227], v[14:17]
	v_mfma_f32_16x16x32_bf16 v[6:9], v[170:173], v[232:235], v[6:9]
	v_mfma_f32_16x16x32_bf16 v[2:5], v[182:185], v[232:235], v[2:5]
	s_setprio 0
	s_barrier
	s_add_i32 s35, s35, 2
	s_add_u32 s42, s42, 0x100
	s_addc_u32 s43, s43, 0
	s_add_u32 s29, s29, 0x100
	s_addc_u32 s34, s34, 0
	s_cmp_gt_u32 s35, 13
